# grid barrier: acquire invalidate pre-issued by wave 1 at barrier entry; L2 writeback dropped in barriers 1,2,3,5 (all stores of those phases now write-through sc1)
# speedup vs baseline: 1.0102x; 1.0001x over previous
; __device__ __forceinline__ void gemv_item(const f32x4 (&wv)[16], int N, int n0, const float* bias, const LAS float* vecs, LAS float* red, float* out, int tid) {
;     ...
;     if (tid < 256) { const int b = tid >> 5, col = tid & 31; float s = 0.f;
; #pragma unroll 8
;       for (int g = 0; g < 64; ++g) s += red[(g * 8 + b) * 32 + col];
;       out[(size_t)b * N + n0 + col] = s + (bias ? bias[n0 + col] : 0.f); }
.LBB0_23:
	s_waitcnt vmcnt(0)
	v_add_f32_e32 v66, v64, v65
	v_lshl_add_u64 v[64:65], s[10:11], 2, v[82:83]
	global_store_dword v[64:65], v66, off sc1

; __device__ __forceinline__ void xcd_barrier(const XcdBarrier& b) {
;     asm volatile("s_waitcnt vmcnt(0)" ::: "memory");
;     __syncthreads();
;     if (threadIdx.x == 0) {
;         unsigned* bar = b.bar;
;         __builtin_amdgcn_s_waitcnt(0);
;         unsigned nloc = b.st[0], nx = b.st[1];
;         if (nloc == 0u) { xcd_barrier_complete(bar, b.x, nloc, nx); b.st[0] = nloc; b.st[1] = nx; }
.LBB0_32:
	s_waitcnt vmcnt(0)
	v_readlane_b32 s0, v255, 3
	v_readlane_b32 s1, v255, 4
	s_barrier
	v_readfirstlane_b32 s4, v208
	s_cmp_lg_u32 s4, 64
	s_cbranch_scc1 .Lgb1_noinv
	buffer_inv sc1
	s_waitcnt vmcnt(0)
.Lgb1_noinv:
	s_and_saveexec_b64 s[6:7], s[0:1]
	s_cbranch_execz .LBB0_95
	s_add_i32 s0, 0, 0x20000
	v_mov_b32_e32 v0, s0
	s_waitcnt vmcnt(0) expcnt(0) lgkmcnt(0)
	ds_read_b32 v2, v0
	s_add_i32 s0, 0, 0x20004
	v_mov_b32_e32 v0, s0
	ds_read_b32 v0, v0
	s_waitcnt lgkmcnt(1)
	v_cmp_ne_u32_e32 vcc, 0, v2
	s_cbranch_vccnz .LBB0_59
	s_add_u32 s8, s24, 0xa0200
	s_addc_u32 s9, s25, 0
	s_add_u32 s10, s24, 0xa0400
	s_addc_u32 s11, s25, 0
	s_add_u32 s12, s24, 0xa0500
	s_addc_u32 s13, s25, 0
	s_add_u32 s14, s24, 0xa0600
	s_addc_u32 s15, s25, 0
	s_add_u32 s16, s24, 0xa0700
	s_addc_u32 s17, s25, 0
	s_add_u32 s18, s24, 0xa0800
	s_addc_u32 s19, s25, 0
	s_add_u32 s20, s24, 0xa0900
	s_addc_u32 s21, s25, 0
	s_add_u32 s22, s24, 0xa0a00
	s_addc_u32 s23, s25, 0
	s_add_u32 s30, s24, 0xa0b00
	s_addc_u32 s31, s25, 0
	s_add_u32 s34, s24, 0xa0c00
	s_addc_u32 s35, s25, 0
	s_add_u32 s36, s24, 0xa0d00
	s_addc_u32 s37, s25, 0
	s_add_u32 s38, s24, 0xa0e00
	s_addc_u32 s39, s25, 0
	s_add_u32 s40, s24, 0xa0f00
	s_addc_u32 s41, s25, 0
	s_add_u32 s42, s24, 0xa1000
	s_load_dword s0, s[96:97], 0x90
	s_addc_u32 s43, s25, 0
	s_add_u32 s44, s24, 0xa1100
	s_addc_u32 s45, s25, 0
	s_add_u32 s46, s24, 0xa1200
	s_addc_u32 s47, s25, 0
	s_waitcnt lgkmcnt(0)
	s_mul_i32 s4, s27, s0
	s_add_u32 s48, s24, 0xa1300
	s_mul_i32 s4, s4, s26
	s_addc_u32 s49, s25, 0
	s_mov_b32 s5, 1
	v_mov_b32_e32 v16, 0
	s_branch .LBB0_36

; __device__ __forceinline__ unsigned xb_ld(unsigned* p)              { return __hip_atomic_load(p, __ATOMIC_RELAXED, __HIP_MEMORY_SCOPE_AGENT); }
; __device__ __forceinline__ unsigned xb_add(unsigned* p, unsigned v) { return __hip_atomic_fetch_add(p, v, __ATOMIC_RELAXED, __HIP_MEMORY_SCOPE_AGENT); }
; #define XB_SPIN(cond, bar) do { unsigned _sp = 0; while (cond) { __builtin_amdgcn_s_sleep(1); \
;     if ((++_sp & 255u) == 0u) { if (xb_ld(&(bar)[XB_TMO])) break; if (_sp > XB_SPIN_CAP) { atomicAdd(&(bar)[XB_TMO], 1u); break; } } } } while (0)
; __device__ __forceinline__ void xcd_barrier(const XcdBarrier& b) {
;     ...
;         const unsigned old = xb_add(&bar[XB_XSUB(b.x)], 1u);
;         const unsigned gen = old / nloc;
;         if (old + 1u == (gen + 1u) * nloc) {
;             __builtin_amdgcn_fence(__ATOMIC_RELEASE, "agent");
;             asm volatile("s_waitcnt vmcnt(0)" ::: "memory");
;             const unsigned og = xb_add(&bar[XB_TOP], 1u);
;             const unsigned tg = og / nx;
;             if (og + 1u == (tg + 1u) * nx) xb_add(&bar[XB_TOPGEN], 1u);
;             else XB_SPIN(xb_ld(&bar[XB_TOPGEN]) == tg, bar);
;             __builtin_amdgcn_fence(__ATOMIC_ACQUIRE, "agent");
;             xb_add(&bar[XB_XGEN(b.x)], 1u);
;             asm volatile("s_waitcnt vmcnt(0)" ::: "memory");
.LBB0_59:
	s_lshl_b32 s0, s33, 8
	v_readlane_b32 s4, v255, 1
	v_readlane_b32 s5, v255, 2
	s_add_u32 s10, s4, s0
	s_addc_u32 s11, s5, 0
	v_mov_b32_e32 v3, 0x1000
	v_mov_b32_e32 v4, 1
	global_atomic_add v3, v3, v4, s[10:11] offset:1024 sc0
	s_waitcnt lgkmcnt(0)
	v_readfirstlane_b32 s12, v2
	v_readfirstlane_b32 s13, v0
	s_mul_i32 s12, s12, 1
	s_mul_i32 s13, s13, 1
	v_mov_b32_e32 v1, 0xa3400
	s_mov_b32 s1, 0
	s_waitcnt vmcnt(0)
	v_readfirstlane_b32 s0, v3
	s_add_i32 s0, s0, 1
	s_cmp_lg_u32 s0, s12
	s_cbranch_scc1 .Lgb1_poll
	global_atomic_add v1, v4, s[24:25]

; __device__ __forceinline__ void gemv_item(const f32x4 (&wv)[16], int N, int n0, const float* bias, const LAS float* vecs, LAS float* red, float* out, int tid) {
;     ...
;     if (tid < 256) { const int b = tid >> 5, col = tid & 31; float s = 0.f;
; #pragma unroll 8
;       for (int g = 0; g < 64; ++g) s += red[(g * 8 + b) * 32 + col];
;       out[(size_t)b * N + n0 + col] = s + (bias ? bias[n0 + col] : 0.f); }
.LBB0_110:
	v_add_u32_e32 v65, s5, v121
	ds_read2st64_b32 v[66:67], v65 offset1:4
	ds_read2st64_b32 v[68:69], v65 offset0:8 offset1:12
	ds_read2st64_b32 v[70:71], v65 offset0:16 offset1:20
	ds_read2st64_b32 v[76:77], v65 offset0:24 offset1:28
	s_addk_i32 s5, 0x2000
	s_waitcnt lgkmcnt(3)
	v_add_f32_e32 v64, v64, v66
	v_add_f32_e32 v64, v64, v67
	s_waitcnt lgkmcnt(2)
	v_add_f32_e32 v64, v64, v68
	v_add_f32_e32 v64, v64, v69
	s_waitcnt lgkmcnt(1)
	v_add_f32_e32 v64, v64, v70
	v_add_f32_e32 v64, v64, v71
	s_waitcnt lgkmcnt(0)
	v_add_f32_e32 v64, v64, v76
	s_cmp_eq_u32 s5, 0x10000
	v_add_f32_e32 v64, v64, v77
	s_cbranch_scc0 .LBB0_110
	s_ashr_i32 s11, s10, 31
	v_add_f32_e32 v66, 0, v64
	v_lshl_add_u64 v[64:65], s[10:11], 2, v[72:73]
	global_store_dword v[64:65], v66, off sc1
	s_branch .LBB0_105

; __device__ __forceinline__ unsigned pk2(float lo, float hi) { return pg8::cvt_pk_bf16(lo, hi); }
; __device__ __forceinline__ void phase1(const Params& p, LAS unsigned char* lds, int tid, int lane, int wave) {
;     ...
;         f32x4 v[2][4]; float ss[2];
; #pragma unroll
;         for (int q = 0; q < 2; ++q) { ss[q] = 0.f;
; #pragma unroll
;             for (int j = 0; j < 4; ++j) { v[q][j] = vn[q][j]; ss[q] += (v[q][j].x * v[q][j].x + v[q][j].y * v[q][j].y) + (v[q][j].z * v[q][j].z + v[q][j].w * v[q][j].w); } }
;         if (row + 2 < r1) {
; #pragma unroll
;             for (int q = 0; q < 2; ++q)
; #pragma unroll
;                 for (int j = 0; j < 4; ++j) vn[q][j] = __builtin_nontemporal_load((const f32x4*)(p.x + (size_t)ROW2(row + 2, q) * D_ + 4 * lane + 256 * j)); }
; #pragma unroll
;         for (int q = 0; q < 2; ++q) ss[q] = xsum12(ss[q]);
; #pragma unroll
;         for (int o = 4; o < 64; o <<= 1) { ss[0] += __shfl_xor(ss[0], o); ss[1] += __shfl_xor(ss[1], o); }
; #pragma unroll
;         for (int q = 0; q < 2; ++q) { const float rstd = rsqrtf(ss[q] * (1.f / D_) + EPS); const int rq = ROW2(row, q);
; #pragma unroll
;             for (int j = 0; j < 4; ++j) { const int col = 4 * lane + 256 * j;
;                 v[q][j] = (v[q][j] * rstd) * gmv[j] + shv[j];
;                 u32x2 w; w.x = pk2(v[q][j].x, v[q][j].y); w.y = pk2(v[q][j].z, v[q][j].w);
;                 *(u32x2*)(hb + (size_t)rq * D_ + col) = w; } }
.LBB0_199:
	v_mov_b32_e32 v120, v77
	v_mov_b32_e32 v121, v93
	v_mov_b32_e32 v118, v76
	v_mov_b32_e32 v119, v92
	v_pk_mul_f32 v[120:121], v[120:121], v[120:121]
	v_mov_b32_e32 v128, v79
	v_mov_b32_e32 v129, v95
	v_pk_fma_f32 v[118:119], v[118:119], v[118:119], v[120:121]
	v_mov_b32_e32 v120, v78
	v_mov_b32_e32 v121, v94
	v_pk_mul_f32 v[128:129], v[128:129], v[128:129]
	v_mov_b32_e32 v130, v75
	v_pk_fma_f32 v[120:121], v[120:121], v[120:121], v[128:129]
	v_mov_b32_e32 v128, v73
	v_mov_b32_e32 v129, v89
	v_pk_add_f32 v[118:119], v[118:119], v[120:121]
	v_mov_b32_e32 v120, v72
	v_mov_b32_e32 v121, v88
	v_pk_mul_f32 v[128:129], v[128:129], v[128:129]
	v_mov_b32_e32 v131, v91
	v_pk_fma_f32 v[120:121], v[120:121], v[120:121], v[128:129]
	v_mov_b32_e32 v128, v74
	v_mov_b32_e32 v129, v90
	v_pk_mul_f32 v[130:131], v[130:131], v[130:131]
	v_mov_b32_e32 v132, v71
	v_pk_fma_f32 v[128:129], v[128:129], v[128:129], v[130:131]
	v_mov_b32_e32 v130, v69
	v_mov_b32_e32 v131, v85
	v_pk_add_f32 v[120:121], v[120:121], v[128:129]
	v_mov_b32_e32 v128, v68
	v_mov_b32_e32 v129, v84
	v_pk_mul_f32 v[130:131], v[130:131], v[130:131]
	v_mov_b32_e32 v133, v87
	v_pk_fma_f32 v[128:129], v[128:129], v[128:129], v[130:131]
	v_mov_b32_e32 v130, v70
	v_mov_b32_e32 v131, v86
	v_pk_mul_f32 v[132:133], v[132:133], v[132:133]
	v_mov_b32_e32 v134, v65
	v_pk_fma_f32 v[130:131], v[130:131], v[130:131], v[132:133]
	v_mov_b32_e32 v135, v81
	v_mov_b32_e32 v138, v67
	v_mov_b32_e32 v139, v83
	v_mov_b32_e32 v132, v64
	v_mov_b32_e32 v133, v80
	v_pk_mul_f32 v[134:135], v[134:135], v[134:135]
	v_mov_b32_e32 v136, v66
	v_mov_b32_e32 v137, v82
	v_pk_mul_f32 v[138:139], v[138:139], v[138:139]
	v_pk_add_f32 v[118:119], v[118:119], v[120:121]
	v_pk_add_f32 v[120:121], v[128:129], v[130:131]
	v_pk_fma_f32 v[128:129], v[136:137], v[136:137], v[138:139]
	v_pk_add_f32 v[118:119], v[118:119], v[120:121]
	v_pk_fma_f32 v[120:121], v[132:133], v[132:133], v[134:135]
	s_add_i32 s0, s14, 1
	v_pk_add_f32 v[120:121], v[120:121], v[128:129]
	s_cmp_lt_i32 s0, s4
	v_pk_add_f32 v[118:119], v[118:119], v[120:121]
	s_cselect_b32 s14, s0, s14
	s_ashr_i32 s15, s14, 31
	v_mov_b32_dpp v121, v119 quad_perm:[1,0,3,2] row_mask:0xf bank_mask:0xf bound_ctrl:1
	v_mov_b32_dpp v120, v118 quad_perm:[1,0,3,2] row_mask:0xf bank_mask:0xf bound_ctrl:1
	v_pk_add_f32 v[118:119], v[118:119], v[120:121]
	s_lshl_b64 s[34:35], s[14:15], 11
	s_nop 0
	v_mov_b32_dpp v121, v119 quad_perm:[2,3,0,1] row_mask:0xf bank_mask:0xf bound_ctrl:1
	v_mov_b32_dpp v120, v118 quad_perm:[2,3,0,1] row_mask:0xf bank_mask:0xf bound_ctrl:1
	v_pk_add_f32 v[118:119], v[118:119], v[120:121]
	ds_bpermute_b32 v121, v97, v119
	ds_bpermute_b32 v120, v97, v118
	s_waitcnt lgkmcnt(0)
	v_pk_add_f32 v[118:119], v[118:119], v[120:121]
	ds_bpermute_b32 v121, v117, v119
	ds_bpermute_b32 v120, v117, v118
	s_waitcnt lgkmcnt(0)
	v_pk_add_f32 v[118:119], v[118:119], v[120:121]
	ds_bpermute_b32 v121, v122, v119
	ds_bpermute_b32 v120, v122, v118
	s_waitcnt lgkmcnt(0)
	v_pk_add_f32 v[118:119], v[118:119], v[120:121]
	ds_bpermute_b32 v121, v123, v119
	ds_bpermute_b32 v120, v123, v118
	s_waitcnt lgkmcnt(0)
	v_pk_add_f32 v[118:119], v[118:119], v[120:121]
	s_nop 0
	v_pk_fma_f32 v[118:119], v[118:119], s[20:21], v[116:117] op_sel_hi:[1,0,0]
	s_nop 0
	v_mul_f32_e32 v120, 0x4b800000, v119
	v_cmp_gt_f32_e32 vcc, s5, v119
	s_nop 1
	v_cndmask_b32_e32 v119, v119, v120, vcc
	v_rsq_f32_e32 v119, v119
	v_lshl_add_u64 v[120:121], s[30:31], 0, v[112:113]
	v_mul_f32_e32 v128, 0x45800000, v119
	v_cndmask_b32_e32 v128, v119, v128, vcc
	v_pk_mul_f32 v[130:131], v[92:93], v[128:129] op_sel_hi:[1,0]
	v_pk_mul_f32 v[92:93], v[94:95], v[128:129] op_sel_hi:[1,0]
	v_add_co_u32_e32 v120, vcc, s21, v120
	v_pk_fma_f32 v[92:93], v[18:19], v[92:93], v[2:3]
	v_pk_fma_f32 v[94:95], v[16:17], v[130:131], v[0:1]
	v_addc_co_u32_e32 v121, vcc, 0, v121, vcc
	v_cvt_pk_bf16_f32 v130, v94, v95
	v_cvt_pk_bf16_f32 v131, v92, v93
	global_store_dwordx2 v[120:121], v[130:131], off sc1
	v_pk_mul_f32 v[130:131], v[88:89], v[128:129] op_sel_hi:[1,0]
	v_pk_mul_f32 v[88:89], v[90:91], v[128:129] op_sel_hi:[1,0]
	v_pk_fma_f32 v[90:91], v[20:21], v[130:131], v[4:5]
	v_pk_fma_f32 v[88:89], v[22:23], v[88:89], v[6:7]
	v_cvt_pk_bf16_f32 v130, v90, v91
	v_mul_f32_e32 v119, 0x4b800000, v118
	v_cvt_pk_bf16_f32 v131, v88, v89
	global_store_dwordx2 v[120:121], v[130:131], off offset:512 sc1
	v_pk_mul_f32 v[130:131], v[84:85], v[128:129] op_sel_hi:[1,0]
	v_pk_mul_f32 v[84:85], v[86:87], v[128:129] op_sel_hi:[1,0]
	v_cmp_gt_f32_e32 vcc, s5, v118
	v_pk_fma_f32 v[84:85], v[26:27], v[84:85], v[10:11]
	v_pk_fma_f32 v[86:87], v[24:25], v[130:131], v[8:9]
	v_cndmask_b32_e32 v118, v118, v119, vcc
	v_cvt_pk_bf16_f32 v130, v86, v87
	v_cvt_pk_bf16_f32 v131, v84, v85
	global_store_dwordx2 v[120:121], v[130:131], off offset:1024 sc1
	v_pk_mul_f32 v[130:131], v[80:81], v[128:129] op_sel_hi:[1,0]
	v_pk_mul_f32 v[80:81], v[82:83], v[128:129] op_sel_hi:[1,0]
	v_rsq_f32_e32 v128, v118
	v_pk_fma_f32 v[82:83], v[28:29], v[130:131], v[12:13]
	v_pk_fma_f32 v[80:81], v[30:31], v[80:81], v[14:15]
	v_cvt_pk_bf16_f32 v118, v82, v83
	s_nop 0
	v_cvt_pk_bf16_f32 v119, v80, v81
	global_store_dwordx2 v[120:121], v[118:119], off offset:1536 sc1
	v_mul_f32_e32 v118, 0x45800000, v128
	v_cndmask_b32_e32 v128, v128, v118, vcc
	v_pk_mul_f32 v[76:77], v[76:77], v[128:129] op_sel_hi:[1,0]
	v_pk_mul_f32 v[78:79], v[78:79], v[128:129] op_sel_hi:[1,0]
	v_pk_fma_f32 v[120:121], v[16:17], v[76:77], v[0:1]
	v_pk_fma_f32 v[78:79], v[18:19], v[78:79], v[2:3]
	v_cvt_pk_bf16_f32 v118, v120, v121
	v_lshl_add_u64 v[76:77], v[108:109], 0, s[34:35]
	v_cvt_pk_bf16_f32 v119, v78, v79
	v_pk_mul_f32 v[72:73], v[72:73], v[128:129] op_sel_hi:[1,0]
	v_pk_mul_f32 v[74:75], v[74:75], v[128:129] op_sel_hi:[1,0]
	global_store_dwordx2 v[76:77], v[118:119], off sc1
	v_pk_fma_f32 v[74:75], v[22:23], v[74:75], v[6:7]
	v_pk_fma_f32 v[118:119], v[20:21], v[72:73], v[4:5]
	v_pk_mul_f32 v[64:65], v[64:65], v[128:129] op_sel_hi:[1,0]
	v_cvt_pk_bf16_f32 v72, v118, v119
	v_cvt_pk_bf16_f32 v73, v74, v75
	global_store_dwordx2 v[76:77], v[72:73], off offset:512 sc1
	v_pk_mul_f32 v[72:73], v[68:69], v[128:129] op_sel_hi:[1,0]
	v_pk_mul_f32 v[68:69], v[70:71], v[128:129] op_sel_hi:[1,0]
	v_pk_fma_f32 v[72:73], v[24:25], v[72:73], v[8:9]
	v_pk_fma_f32 v[68:69], v[26:27], v[68:69], v[10:11]
	v_cvt_pk_bf16_f32 v70, v72, v73
	v_pk_mul_f32 v[66:67], v[66:67], v[128:129] op_sel_hi:[1,0]
	v_cvt_pk_bf16_f32 v71, v68, v69
	v_add_u32_e32 v128, 0, v98
	global_store_dwordx2 v[76:77], v[70:71], off offset:1024 sc1
	v_pk_fma_f32 v[66:67], v[30:31], v[66:67], v[14:15]
	v_pk_fma_f32 v[70:71], v[28:29], v[64:65], v[12:13]
	s_nop 0
	v_cvt_pk_bf16_f32 v64, v70, v71
	v_cvt_pk_bf16_f32 v65, v66, v67
	ds_read_b128 v[130:133], v128
	ds_read_b128 v[134:137], v128 offset:1024
	global_store_dwordx2 v[76:77], v[64:65], off offset:1536 sc1
	s_waitcnt lgkmcnt(1)
; #define LAS __attribute__((address_space(3)))
; __device__ __forceinline__ void phase1(const Params& p, LAS unsigned char* lds, int tid, int lane, int wave) {
;     ...
;         float f[2][8];
; #pragma unroll
;         for (int h = 0; h < 8; ++h) { float s0 = 0.f, s1 = 0.f;
; #pragma unroll
;             for (int j = 0; j < 4; ++j) { const f32x4 w = *(const LAS f32x4*)(wf + h * 1024 + 4 * lane + 256 * j);
;                 s0 += (v[0][j].x * w.x + v[0][j].y * w.y) + (v[0][j].z * w.z + v[0][j].w * w.w); s1 += (v[1][j].x * w.x + v[1][j].y * w.y) + (v[1][j].z * w.z + v[1][j].w * w.w); }
;             f[0][h] = s0; f[1][h] = s1; }
	v_mul_f32_e32 v129, v95, v131
	v_mul_f32_e32 v131, v121, v131
	v_fmac_f32_e32 v129, v94, v130
	v_fmac_f32_e32 v131, v120, v130
	v_mul_f32_e32 v130, v79, v133
	v_mul_f32_e32 v138, v93, v133
	v_fmac_f32_e32 v130, v78, v132
	v_fmac_f32_e32 v138, v92, v132
	v_add_f32_e32 v130, v131, v130
	v_add_f32_e32 v129, v129, v138
	v_add_f32_e32 v138, 0, v130
	s_waitcnt lgkmcnt(0)
	v_mul_f32_e32 v130, v91, v135
	v_mul_f32_e32 v131, v89, v137
	v_fmac_f32_e32 v130, v90, v134
	v_fmac_f32_e32 v131, v88, v136
	v_add_f32_e32 v129, 0, v129
	v_add_f32_e32 v130, v130, v131
	v_mul_f32_e32 v135, v119, v135
	v_add_f32_e32 v129, v129, v130
	v_fmac_f32_e32 v135, v118, v134
	v_mul_f32_e32 v134, v75, v137
	ds_read_b128 v[130:133], v128 offset:2048
	v_fmac_f32_e32 v134, v74, v136
	v_add_f32_e32 v134, v135, v134
	v_add_f32_e32 v138, v138, v134
	ds_read_b128 v[134:137], v128 offset:3072
	s_waitcnt lgkmcnt(1)
	v_mul_f32_e32 v139, v87, v131
	v_mul_f32_e32 v131, v73, v131
	v_fmac_f32_e32 v139, v86, v130
	v_fmac_f32_e32 v131, v72, v130
	v_mul_f32_e32 v130, v69, v133
	v_mul_f32_e32 v140, v85, v133
	v_fmac_f32_e32 v130, v68, v132
	v_fmac_f32_e32 v140, v84, v132
	v_add_f32_e32 v130, v131, v130
	s_waitcnt lgkmcnt(0)
	v_mul_f32_e32 v131, v83, v135
	v_mul_f32_e32 v132, v81, v137
	v_add_f32_e32 v139, v139, v140
	v_fmac_f32_e32 v131, v82, v134
	v_fmac_f32_e32 v132, v80, v136
	v_add_f32_e32 v129, v129, v139
	v_add_f32_e32 v131, v131, v132
	v_add_f32_e32 v129, v129, v131
	v_mul_f32_e32 v131, v71, v135
	v_fmac_f32_e32 v131, v70, v134
	ds_read_b128 v[132:135], v128 offset:4096
	v_mul_f32_e32 v137, v67, v137
	v_fmac_f32_e32 v137, v66, v136
	v_add_f32_e32 v130, v138, v130
	v_add_f32_e32 v131, v131, v137
	ds_read_b128 v[136:139], v128 offset:5120
	v_add_f32_e32 v130, v130, v131
	s_waitcnt lgkmcnt(1)
	v_mul_f32_e32 v131, v95, v133
	v_mul_f32_e32 v133, v121, v133
	v_fmac_f32_e32 v131, v94, v132
	v_fmac_f32_e32 v133, v120, v132
	v_mul_f32_e32 v132, v79, v135
	v_mul_f32_e32 v140, v93, v135
	v_fmac_f32_e32 v132, v78, v134
	v_fmac_f32_e32 v140, v92, v134
	v_add_f32_e32 v132, v133, v132
	v_add_f32_e32 v131, v131, v140
	v_add_f32_e32 v140, 0, v132
	s_waitcnt lgkmcnt(0)
	v_mul_f32_e32 v132, v91, v137
	v_mul_f32_e32 v133, v89, v139
	v_fmac_f32_e32 v132, v90, v136
	v_fmac_f32_e32 v133, v88, v138
	v_add_f32_e32 v131, 0, v131
	v_add_f32_e32 v132, v132, v133
	v_mul_f32_e32 v137, v119, v137
	v_add_f32_e32 v131, v131, v132
	v_fmac_f32_e32 v137, v118, v136
	v_mul_f32_e32 v136, v75, v139
	ds_read_b128 v[132:135], v128 offset:6144
	v_fmac_f32_e32 v136, v74, v138
	v_add_f32_e32 v136, v137, v136
	v_add_f32_e32 v140, v140, v136
	ds_read_b128 v[136:139], v128 offset:7168
	s_waitcnt lgkmcnt(1)
	v_mul_f32_e32 v141, v87, v133
	v_mul_f32_e32 v133, v73, v133
	v_fmac_f32_e32 v141, v86, v132
	v_fmac_f32_e32 v133, v72, v132
	v_mul_f32_e32 v132, v69, v135
	v_mul_f32_e32 v142, v85, v135
	v_fmac_f32_e32 v132, v68, v134
	v_fmac_f32_e32 v142, v84, v134
	v_add_f32_e32 v132, v133, v132
	s_waitcnt lgkmcnt(0)
	v_mul_f32_e32 v133, v83, v137
	v_mul_f32_e32 v134, v81, v139
	v_add_f32_e32 v141, v141, v142
	v_fmac_f32_e32 v133, v82, v136
	v_fmac_f32_e32 v134, v80, v138
	v_add_f32_e32 v131, v131, v141
	v_add_f32_e32 v133, v133, v134
	v_add_f32_e32 v131, v131, v133
	v_mul_f32_e32 v133, v71, v137
	v_fmac_f32_e32 v133, v70, v136
	ds_read_b128 v[134:137], v128 offset:8192
	v_mul_f32_e32 v139, v67, v139
	v_fmac_f32_e32 v139, v66, v138
	v_add_f32_e32 v132, v140, v132
	v_add_f32_e32 v133, v133, v139
	ds_read_b128 v[138:141], v128 offset:9216
	v_add_f32_e32 v132, v132, v133
	s_waitcnt lgkmcnt(1)
	v_mul_f32_e32 v133, v95, v135
	v_mul_f32_e32 v135, v121, v135
	v_fmac_f32_e32 v133, v94, v134
	v_fmac_f32_e32 v135, v120, v134
	v_mul_f32_e32 v134, v79, v137
	v_mul_f32_e32 v142, v93, v137
	v_fmac_f32_e32 v134, v78, v136
	v_fmac_f32_e32 v142, v92, v136
	v_add_f32_e32 v134, v135, v134
	v_add_f32_e32 v133, v133, v142
	v_add_f32_e32 v142, 0, v134
	s_waitcnt lgkmcnt(0)
	v_mul_f32_e32 v134, v91, v139
	v_mul_f32_e32 v135, v89, v141
	v_fmac_f32_e32 v134, v90, v138
	v_fmac_f32_e32 v135, v88, v140
	v_add_f32_e32 v133, 0, v133
	v_add_f32_e32 v134, v134, v135
	v_mul_f32_e32 v139, v119, v139
	v_add_f32_e32 v133, v133, v134
	v_fmac_f32_e32 v139, v118, v138
	v_mul_f32_e32 v138, v75, v141
	ds_read_b128 v[134:137], v128 offset:10240
	v_fmac_f32_e32 v138, v74, v140
	v_add_f32_e32 v138, v139, v138
	v_add_f32_e32 v142, v142, v138
	ds_read_b128 v[138:141], v128 offset:11264
	s_waitcnt lgkmcnt(1)
	v_mul_f32_e32 v143, v87, v135
	v_mul_f32_e32 v135, v73, v135
	v_fmac_f32_e32 v143, v86, v134
	v_fmac_f32_e32 v135, v72, v134
	v_mul_f32_e32 v134, v69, v137
	v_mul_f32_e32 v144, v85, v137
	v_fmac_f32_e32 v134, v68, v136
	v_fmac_f32_e32 v144, v84, v136
	v_add_f32_e32 v134, v135, v134
	s_waitcnt lgkmcnt(0)
	v_mul_f32_e32 v135, v83, v139
	v_mul_f32_e32 v136, v81, v141
	v_add_f32_e32 v143, v143, v144
	v_fmac_f32_e32 v135, v82, v138
	v_fmac_f32_e32 v136, v80, v140
	v_add_f32_e32 v133, v133, v143
	v_add_f32_e32 v135, v135, v136
	v_add_f32_e32 v133, v133, v135
	v_mul_f32_e32 v135, v71, v139
	v_fmac_f32_e32 v135, v70, v138
	ds_read_b128 v[136:139], v128 offset:12288
	v_mul_f32_e32 v141, v67, v141
	v_fmac_f32_e32 v141, v66, v140
	v_add_f32_e32 v134, v142, v134
	v_add_f32_e32 v135, v135, v141
	ds_read_b128 v[140:143], v128 offset:13312
	v_add_f32_e32 v134, v134, v135
	s_waitcnt lgkmcnt(1)
	v_mul_f32_e32 v135, v95, v137
	v_mul_f32_e32 v137, v121, v137
	v_fmac_f32_e32 v135, v94, v136
	v_fmac_f32_e32 v137, v120, v136
	v_mul_f32_e32 v136, v79, v139
	v_mul_f32_e32 v144, v93, v139
	v_fmac_f32_e32 v136, v78, v138
	v_fmac_f32_e32 v144, v92, v138
	v_add_f32_e32 v136, v137, v136
	v_add_f32_e32 v135, v135, v144
	v_add_f32_e32 v144, 0, v136
	s_waitcnt lgkmcnt(0)
; #define LAS __attribute__((address_space(3)))
; __device__ __forceinline__ void phase1(const Params& p, LAS unsigned char* lds, int tid, int lane, int wave) {
;     ...
;         float f[2][8];
; #pragma unroll
;         for (int h = 0; h < 8; ++h) { float s0 = 0.f, s1 = 0.f;
; #pragma unroll
;             for (int j = 0; j < 4; ++j) { const f32x4 w = *(const LAS f32x4*)(wf + h * 1024 + 4 * lane + 256 * j);
;                 s0 += (v[0][j].x * w.x + v[0][j].y * w.y) + (v[0][j].z * w.z + v[0][j].w * w.w); s1 += (v[1][j].x * w.x + v[1][j].y * w.y) + (v[1][j].z * w.z + v[1][j].w * w.w); }
;             f[0][h] = s0; f[1][h] = s1; }
	v_mul_f32_e32 v136, v91, v141
	v_mul_f32_e32 v137, v89, v143
	v_fmac_f32_e32 v136, v90, v140
	v_fmac_f32_e32 v137, v88, v142
	v_add_f32_e32 v135, 0, v135
	v_add_f32_e32 v136, v136, v137
	v_add_f32_e32 v135, v135, v136
	v_mul_f32_e32 v141, v119, v141
	ds_read_b128 v[136:139], v128 offset:14336
	v_fmac_f32_e32 v141, v118, v140
	v_mul_f32_e32 v140, v75, v143
	v_fmac_f32_e32 v140, v74, v142
	v_add_f32_e32 v140, v141, v140
	v_add_f32_e32 v144, v144, v140
	ds_read_b128 v[140:143], v128 offset:15360
	s_waitcnt lgkmcnt(1)
	v_mul_f32_e32 v145, v87, v137
	v_mul_f32_e32 v137, v73, v137
	v_fmac_f32_e32 v145, v86, v136
	v_fmac_f32_e32 v137, v72, v136
	v_mul_f32_e32 v136, v69, v139
	v_fmac_f32_e32 v136, v68, v138
	v_mul_f32_e32 v146, v85, v139
	v_add_f32_e32 v136, v137, v136
	v_fmac_f32_e32 v146, v84, v138
	v_add_f32_e32 v144, v144, v136
	s_waitcnt lgkmcnt(0)
	v_mul_f32_e32 v136, v83, v141
	v_mul_f32_e32 v137, v81, v143
	v_add_f32_e32 v145, v145, v146
	v_fmac_f32_e32 v136, v82, v140
	v_fmac_f32_e32 v137, v80, v142
	v_add_f32_e32 v135, v135, v145
	v_add_f32_e32 v136, v136, v137
	v_add_f32_e32 v135, v135, v136
	v_mul_f32_e32 v141, v71, v141
	ds_read_b128 v[136:139], v128 offset:16384
	v_fmac_f32_e32 v141, v70, v140
	v_mul_f32_e32 v140, v67, v143
	v_fmac_f32_e32 v140, v66, v142
	v_add_f32_e32 v140, v141, v140
	v_add_f32_e32 v144, v144, v140
	ds_read_b128 v[140:143], v128 offset:17408
	s_waitcnt lgkmcnt(1)
	v_mul_f32_e32 v145, v95, v137
	v_mul_f32_e32 v137, v121, v137
	v_fmac_f32_e32 v145, v94, v136
	v_fmac_f32_e32 v137, v120, v136
	v_mul_f32_e32 v136, v79, v139
	v_mul_f32_e32 v146, v93, v139
	v_fmac_f32_e32 v136, v78, v138
	v_fmac_f32_e32 v146, v92, v138
	v_add_f32_e32 v136, v137, v136
	v_add_f32_e32 v145, v145, v146
	v_add_f32_e32 v146, 0, v136
	s_waitcnt lgkmcnt(0)
	v_mul_f32_e32 v136, v91, v141
	v_mul_f32_e32 v137, v89, v143
	v_fmac_f32_e32 v136, v90, v140
	v_fmac_f32_e32 v137, v88, v142
	v_add_f32_e32 v145, 0, v145
	v_add_f32_e32 v136, v136, v137
	v_add_f32_e32 v145, v145, v136
	v_mul_f32_e32 v141, v119, v141
	ds_read_b128 v[136:139], v128 offset:18432
	v_fmac_f32_e32 v141, v118, v140
	v_mul_f32_e32 v140, v75, v143
	v_fmac_f32_e32 v140, v74, v142
	v_add_f32_e32 v140, v141, v140
	v_add_f32_e32 v146, v146, v140
	ds_read_b128 v[140:143], v128 offset:19456
	s_waitcnt lgkmcnt(1)
	v_mul_f32_e32 v147, v87, v137
	v_mul_f32_e32 v137, v73, v137
	v_fmac_f32_e32 v147, v86, v136
	v_fmac_f32_e32 v137, v72, v136
	v_mul_f32_e32 v136, v69, v139
	v_fmac_f32_e32 v136, v68, v138
	v_mul_f32_e32 v148, v85, v139
	v_add_f32_e32 v136, v137, v136
	v_fmac_f32_e32 v148, v84, v138
	v_add_f32_e32 v146, v146, v136
	s_waitcnt lgkmcnt(0)
	v_mul_f32_e32 v136, v83, v141
	v_mul_f32_e32 v137, v81, v143
	v_add_f32_e32 v147, v147, v148
	v_fmac_f32_e32 v136, v82, v140
	v_fmac_f32_e32 v137, v80, v142
	v_add_f32_e32 v145, v145, v147
	v_add_f32_e32 v136, v136, v137
	v_add_f32_e32 v145, v145, v136
	v_mul_f32_e32 v141, v71, v141
	ds_read_b128 v[136:139], v128 offset:20480
	v_fmac_f32_e32 v141, v70, v140
	v_mul_f32_e32 v140, v67, v143
	v_fmac_f32_e32 v140, v66, v142
	v_add_f32_e32 v140, v141, v140
	v_add_f32_e32 v146, v146, v140
	ds_read_b128 v[140:143], v128 offset:21504
	s_waitcnt lgkmcnt(1)
	v_mul_f32_e32 v147, v95, v137
	v_mul_f32_e32 v137, v121, v137
	v_fmac_f32_e32 v147, v94, v136
	v_fmac_f32_e32 v137, v120, v136
	v_mul_f32_e32 v136, v79, v139
	v_mul_f32_e32 v148, v93, v139
	v_fmac_f32_e32 v136, v78, v138
	v_fmac_f32_e32 v148, v92, v138
	v_add_f32_e32 v136, v137, v136
	v_add_f32_e32 v147, v147, v148
	v_add_f32_e32 v148, 0, v136
	s_waitcnt lgkmcnt(0)
	v_mul_f32_e32 v136, v91, v141
	v_mul_f32_e32 v137, v89, v143
	v_fmac_f32_e32 v136, v90, v140
	v_fmac_f32_e32 v137, v88, v142
	v_add_f32_e32 v147, 0, v147
	v_add_f32_e32 v136, v136, v137
	v_add_f32_e32 v147, v147, v136
	v_mul_f32_e32 v141, v119, v141
	ds_read_b128 v[136:139], v128 offset:22528
	v_fmac_f32_e32 v141, v118, v140
	v_mul_f32_e32 v140, v75, v143
	v_fmac_f32_e32 v140, v74, v142
	v_add_f32_e32 v140, v141, v140
	v_add_f32_e32 v148, v148, v140
	ds_read_b128 v[140:143], v128 offset:23552
	s_waitcnt lgkmcnt(1)
	v_mul_f32_e32 v149, v87, v137
	v_mul_f32_e32 v137, v73, v137
	v_fmac_f32_e32 v149, v86, v136
	v_fmac_f32_e32 v137, v72, v136
	v_mul_f32_e32 v136, v69, v139
	v_fmac_f32_e32 v136, v68, v138
	v_mul_f32_e32 v150, v85, v139
	v_add_f32_e32 v136, v137, v136
	v_fmac_f32_e32 v150, v84, v138
	v_add_f32_e32 v148, v148, v136
	s_waitcnt lgkmcnt(0)
	v_mul_f32_e32 v136, v83, v141
	v_mul_f32_e32 v137, v81, v143
	v_add_f32_e32 v149, v149, v150
	v_fmac_f32_e32 v136, v82, v140
	v_fmac_f32_e32 v137, v80, v142
	v_add_f32_e32 v147, v147, v149
	v_add_f32_e32 v136, v136, v137
	v_add_f32_e32 v147, v147, v136
	v_mul_f32_e32 v141, v71, v141
	ds_read_b128 v[136:139], v128 offset:24576
	v_fmac_f32_e32 v141, v70, v140
	v_mul_f32_e32 v140, v67, v143
	v_fmac_f32_e32 v140, v66, v142
	v_add_f32_e32 v140, v141, v140
	v_add_f32_e32 v148, v148, v140
	ds_read_b128 v[140:143], v128 offset:25600
	s_waitcnt lgkmcnt(1)
	v_mul_f32_e32 v149, v95, v137
	v_mul_f32_e32 v137, v121, v137
	v_fmac_f32_e32 v149, v94, v136
	v_fmac_f32_e32 v137, v120, v136
	v_mul_f32_e32 v136, v79, v139
	v_mul_f32_e32 v150, v93, v139
	v_fmac_f32_e32 v136, v78, v138
	v_fmac_f32_e32 v150, v92, v138
	v_add_f32_e32 v136, v137, v136
	v_add_f32_e32 v149, v149, v150
	v_add_f32_e32 v150, 0, v136
	s_waitcnt lgkmcnt(0)
	v_mul_f32_e32 v136, v91, v141
	v_mul_f32_e32 v137, v89, v143
	v_fmac_f32_e32 v136, v90, v140
	v_fmac_f32_e32 v137, v88, v142
	v_add_f32_e32 v149, 0, v149
	v_add_f32_e32 v136, v136, v137
	v_add_f32_e32 v149, v149, v136
	v_mul_f32_e32 v141, v119, v141
	ds_read_b128 v[136:139], v128 offset:26624
	v_fmac_f32_e32 v141, v118, v140
	v_mul_f32_e32 v140, v75, v143
	v_fmac_f32_e32 v140, v74, v142
	v_add_f32_e32 v140, v141, v140
	v_add_f32_e32 v150, v150, v140
	ds_read_b128 v[140:143], v128 offset:27648
	s_waitcnt lgkmcnt(1)
; __device__ __forceinline__ void phase1(const Params& p, LAS unsigned char* lds, int tid, int lane, int wave) {
;     ...
;         float g4[2][4], g2[2][2], z[2];
; #pragma unroll
;         for (int i = 0; i < 4; ++i)
; #pragma unroll
;             for (int q = 0; q < 2; ++q) { const float send = b5 ? f[q][i] : f[q][4 + i], keep = b5 ? f[q][4 + i] : f[q][i]; g4[q][i] = keep + __shfl_xor(send, 32); }
; #pragma unroll
;         for (int i = 0; i < 2; ++i)
; #pragma unroll
;             for (int q = 0; q < 2; ++q) { const float send = b4 ? g4[q][i] : g4[q][2 + i], keep = b4 ? g4[q][2 + i] : g4[q][i]; g2[q][i] = keep + __shfl_xor(send, 16); }
; #pragma unroll
;         for (int q = 0; q < 2; ++q) { const float send = b3 ? g2[q][0] : g2[q][1], keep = b3 ? g2[q][1] : g2[q][0]; z[q] = keep + __shfl_xor(send, 8); }
; #pragma unroll
;         for (int q = 0; q < 2; ++q) z[q] = xsum12(z[q]);
;         z[0] += __shfl_xor(z[0], 4); z[1] += __shfl_xor(z[1], 4);
;         if ((lane & 7) == 0) { const int h = lane >> 3; const float bf_ = p.b_f[h];
; #pragma unroll
;             for (int q = 0; q < 2; ++q) { const float zz = z[q] + bf_; logf[(size_t)ROW2(row, q) * 8 + h] = fminf(zz, 0.f) - __logf(1.f + __expf(-fabsf(zz))); } }
	v_mul_f32_e32 v151, v87, v137
	v_mul_f32_e32 v137, v73, v137
	v_fmac_f32_e32 v151, v86, v136
	v_fmac_f32_e32 v137, v72, v136
	v_mul_f32_e32 v136, v69, v139
	v_fmac_f32_e32 v136, v68, v138
	v_mul_f32_e32 v152, v85, v139
	v_add_f32_e32 v136, v137, v136
	v_fmac_f32_e32 v152, v84, v138
	v_add_f32_e32 v150, v150, v136
	s_waitcnt lgkmcnt(0)
	v_mul_f32_e32 v136, v83, v141
	v_mul_f32_e32 v137, v81, v143
	v_add_f32_e32 v151, v151, v152
	v_fmac_f32_e32 v136, v82, v140
	v_fmac_f32_e32 v137, v80, v142
	v_add_f32_e32 v149, v149, v151
	v_add_f32_e32 v136, v136, v137
	v_add_f32_e32 v149, v149, v136
	v_mul_f32_e32 v141, v71, v141
	ds_read_b128 v[136:139], v128 offset:28672
	v_fmac_f32_e32 v141, v70, v140
	v_mul_f32_e32 v140, v67, v143
	v_fmac_f32_e32 v140, v66, v142
	v_add_f32_e32 v140, v141, v140
	v_add_f32_e32 v150, v150, v140
	ds_read_b128 v[140:143], v128 offset:29696
	s_waitcnt lgkmcnt(1)
	v_mul_f32_e32 v95, v95, v137
	v_mul_f32_e32 v93, v93, v139
	v_fmac_f32_e32 v95, v94, v136
	v_fmac_f32_e32 v93, v92, v138
	v_add_f32_e32 v92, v95, v93
	v_mul_f32_e32 v93, v121, v137
	v_mul_f32_e32 v79, v79, v139
	v_fmac_f32_e32 v93, v120, v136
	v_fmac_f32_e32 v79, v78, v138
	v_add_f32_e32 v78, v93, v79
	s_waitcnt lgkmcnt(0)
	v_mul_f32_e32 v79, v91, v141
	v_mul_f32_e32 v89, v89, v143
	v_fmac_f32_e32 v79, v90, v140
	v_fmac_f32_e32 v89, v88, v142
	v_add_f32_e32 v92, 0, v92
	v_add_f32_e32 v79, v79, v89
	v_add_f32_e32 v79, v92, v79
	v_mul_f32_e32 v92, v119, v141
	v_mul_f32_e32 v75, v75, v143
	v_fmac_f32_e32 v92, v118, v140
	v_fmac_f32_e32 v75, v74, v142
	ds_read_b128 v[88:91], v128 offset:30720
	v_add_f32_e32 v74, v92, v75
	ds_read_b128 v[92:95], v128 offset:31744
	v_add_f32_e32 v78, 0, v78
	v_add_f32_e32 v74, v78, v74
	s_waitcnt lgkmcnt(1)
	v_mul_f32_e32 v73, v73, v89
	v_mul_f32_e32 v69, v69, v91
	s_waitcnt lgkmcnt(0)
	v_mul_f32_e32 v71, v71, v93
	v_mul_f32_e32 v67, v67, v95
	v_fmac_f32_e32 v71, v70, v92
	v_fmac_f32_e32 v67, v66, v94
	v_add_f32_e32 v66, v71, v67
	v_cndmask_b32_e64 v67, v129, v145, s[6:7]
	ds_bpermute_b32 v67, v123, v67
	v_cndmask_b32_e64 v70, v130, v146, s[6:7]
	v_fmac_f32_e32 v73, v72, v88
	v_fmac_f32_e32 v69, v68, v90
	ds_bpermute_b32 v70, v123, v70
	v_cndmask_b32_e64 v71, v131, v147, s[6:7]
	v_add_f32_e32 v68, v73, v69
	ds_bpermute_b32 v71, v123, v71
	v_add_f32_e32 v68, v74, v68
	v_add_f32_e32 v66, v68, v66
	v_cndmask_b32_e64 v68, v145, v129, s[6:7]
	s_waitcnt lgkmcnt(2)
	v_add_f32_e32 v67, v68, v67
	v_cndmask_b32_e64 v68, v146, v130, s[6:7]
	s_waitcnt lgkmcnt(1)
	v_add_f32_e32 v68, v68, v70
	v_cndmask_b32_e64 v70, v147, v131, s[6:7]
	s_waitcnt lgkmcnt(0)
	v_add_f32_e32 v70, v70, v71
	v_cndmask_b32_e64 v71, v132, v148, s[6:7]
	ds_bpermute_b32 v71, v123, v71
	v_cndmask_b32_e64 v73, v133, v149, s[6:7]
	ds_bpermute_b32 v73, v123, v73
	v_cndmask_b32_e64 v74, v134, v150, s[6:7]
	v_mul_f32_e32 v75, v87, v89
	v_mul_f32_e32 v78, v85, v91
	v_mul_f32_e32 v69, v83, v93
	v_mul_f32_e32 v72, v81, v95
	ds_bpermute_b32 v74, v123, v74
	v_fmac_f32_e32 v75, v86, v88
	v_fmac_f32_e32 v78, v84, v90
	v_fmac_f32_e32 v69, v82, v92
	v_fmac_f32_e32 v72, v80, v94
	v_add_f32_e32 v75, v75, v78
	v_add_f32_e32 v69, v69, v72
	v_cndmask_b32_e64 v72, v148, v132, s[6:7]
	v_add_f32_e32 v75, v79, v75
	s_waitcnt lgkmcnt(2)
	v_add_f32_e32 v71, v72, v71
	v_cndmask_b32_e64 v72, v149, v133, s[6:7]
	v_add_f32_e32 v69, v75, v69
	s_waitcnt lgkmcnt(1)
	v_add_f32_e32 v72, v72, v73
	v_cndmask_b32_e64 v73, v150, v134, s[6:7]
	s_waitcnt lgkmcnt(0)
	v_add_f32_e32 v73, v73, v74
	v_cndmask_b32_e64 v74, v135, v69, s[6:7]
	v_cndmask_b32_e64 v75, v144, v66, s[6:7]
	ds_bpermute_b32 v74, v123, v74
	ds_bpermute_b32 v75, v123, v75
	v_cndmask_b32_e64 v69, v69, v135, s[6:7]
	v_cndmask_b32_e64 v66, v66, v144, s[6:7]
	v_cndmask_b32_e64 v78, v67, v72, s[8:9]
	s_waitcnt lgkmcnt(1)
	v_add_f32_e32 v69, v69, v74
	s_waitcnt lgkmcnt(0)
	v_add_f32_e32 v66, v66, v75
	v_cndmask_b32_e64 v67, v72, v67, s[8:9]
	v_cndmask_b32_e64 v72, v68, v73, s[8:9]
	v_cndmask_b32_e64 v68, v73, v68, s[8:9]
	v_cndmask_b32_e64 v73, v70, v69, s[8:9]
	v_cndmask_b32_e64 v74, v71, v66, s[8:9]
	ds_bpermute_b32 v78, v122, v78
	ds_bpermute_b32 v72, v122, v72
	ds_bpermute_b32 v73, v122, v73
	ds_bpermute_b32 v74, v122, v74
	v_cndmask_b32_e64 v69, v69, v70, s[8:9]
	v_cndmask_b32_e64 v66, v66, v71, s[8:9]
	s_waitcnt lgkmcnt(3)
	v_add_f32_e32 v67, v67, v78
	s_waitcnt lgkmcnt(2)
	v_add_f32_e32 v68, v68, v72
	s_waitcnt lgkmcnt(1)
	v_add_f32_e32 v69, v69, v73
	s_waitcnt lgkmcnt(0)
	v_add_f32_e32 v66, v66, v74
	v_cndmask_b32_e64 v70, v67, v69, s[10:11]
	v_cndmask_b32_e64 v71, v68, v66, s[10:11]
	ds_bpermute_b32 v70, v117, v70
	ds_bpermute_b32 v71, v117, v71
	v_cndmask_b32_e64 v67, v69, v67, s[10:11]
	v_cndmask_b32_e64 v66, v66, v68, s[10:11]
	s_waitcnt lgkmcnt(1)
	v_add_f32_e32 v67, v67, v70
	s_waitcnt lgkmcnt(0)
	v_add_f32_e32 v68, v66, v71
	v_add_f32_dpp v66, v67, v67 quad_perm:[1,0,3,2] row_mask:0xf bank_mask:0xf bound_ctrl:1
	s_nop 0
	v_add_f32_dpp v67, v68, v68 quad_perm:[1,0,3,2] row_mask:0xf bank_mask:0xf bound_ctrl:1
	v_add_f32_dpp v66, v66, v66 quad_perm:[2,3,0,1] row_mask:0xf bank_mask:0xf bound_ctrl:1
	ds_bpermute_b32 v68, v97, v66
	v_add_f32_dpp v67, v67, v67 quad_perm:[2,3,0,1] row_mask:0xf bank_mask:0xf bound_ctrl:1
	ds_bpermute_b32 v69, v97, v67
	s_and_saveexec_b64 s[34:35], s[12:13]
	s_cbranch_execz .LBB0_194
	global_load_dword v70, v[106:107], off
	s_waitcnt lgkmcnt(1)
	v_add_f32_e32 v68, v66, v68
	s_waitcnt lgkmcnt(0)
	v_add_f32_e32 v69, v67, v69
	s_lshl_b64 s[14:15], s[14:15], 5
	v_lshl_add_u64 v[66:67], v[102:103], 0, s[14:15]
	v_lshl_add_u64 v[64:65], s[30:31], 0, v[110:111]
	s_waitcnt vmcnt(0)
	v_add_f32_e32 v68, v68, v70
	v_add_f32_e32 v69, v69, v70
	v_mul_f32_e64 v70, |v68|, s28
	v_mul_f32_e64 v71, |v69|, s28
	v_exp_f32_e32 v70, v70
	v_exp_f32_e32 v71, v71
	v_min_f32_e32 v68, 0, v68
	v_min_f32_e32 v69, 0, v69
	v_add_f32_e32 v70, 1.0, v70
	v_add_f32_e32 v71, 1.0, v71
	v_cmp_gt_f32_e32 vcc, s5, v70
	v_cmp_gt_f32_e64 s[14:15], s5, v71
	s_nop 0
	v_cndmask_b32_e64 v72, 0, 32, vcc
	v_cndmask_b32_e64 v73, 0, 32, s[14:15]
	v_ldexp_f32 v70, v70, v72
	v_ldexp_f32 v71, v71, v73
	v_log_f32_e32 v70, v70
	v_log_f32_e32 v71, v71
	v_cndmask_b32_e32 v72, 0, v127, vcc
	v_cndmask_b32_e64 v73, 0, v127, s[14:15]
	v_mul_f32_e32 v74, 0x3f317217, v70
	v_mul_f32_e32 v75, 0x3f317217, v71
	v_fma_f32 v74, v70, s29, -v74
	v_fma_f32 v75, v71, s29, -v75
	v_fmac_f32_e32 v74, 0x3377d1cf, v70
	v_fmac_f32_e32 v75, 0x3377d1cf, v71
	v_fmac_f32_e32 v74, 0x3f317217, v70
	v_cmp_lt_f32_e64 vcc, |v70|, s36
	v_fmac_f32_e32 v75, 0x3f317217, v71
	s_nop 0
	v_cndmask_b32_e32 v70, v70, v74, vcc
	v_cmp_lt_f32_e64 vcc, |v71|, s36
	v_sub_f32_e32 v70, v70, v72
	v_sub_f32_e32 v68, v68, v70
	v_cndmask_b32_e32 v71, v71, v75, vcc
	v_sub_f32_e32 v71, v71, v73
	v_sub_f32_e32 v69, v69, v71
	global_store_dword v[64:65], v68, off sc1
	global_store_dword v[66:67], v69, off sc1
	s_branch .LBB0_194
; __device__ __forceinline__ void xcd_barrier(const XcdBarrier& b) {
;     asm volatile("s_waitcnt vmcnt(0)" ::: "memory");
;     __syncthreads();
;     if (threadIdx.x == 0) {
;         unsigned* bar = b.bar;
;         __builtin_amdgcn_s_waitcnt(0);
;         unsigned nloc = b.st[0], nx = b.st[1];
;         if (nloc == 0u) { xcd_barrier_complete(bar, b.x, nloc, nx); b.st[0] = nloc; b.st[1] = nx; }
.LBB0_201:
	s_barrier
	s_waitcnt vmcnt(0)
	v_readlane_b32 s0, v255, 3
	v_readlane_b32 s1, v255, 4
	s_barrier
	v_readfirstlane_b32 s4, v208
	s_cmp_lg_u32 s4, 64
	s_cbranch_scc1 .Lgb2_noinv
	buffer_inv sc1
	s_waitcnt vmcnt(0)
.Lgb2_noinv:
	s_and_saveexec_b64 s[8:9], s[0:1]
	s_cbranch_execz .LBB0_253
	s_add_i32 s0, 0, 0x20000
	v_mov_b32_e32 v0, s0
	s_waitcnt vmcnt(0) expcnt(0) lgkmcnt(0)
	ds_read_b32 v2, v0
	s_add_i32 s0, 0, 0x20004
	v_mov_b32_e32 v0, s0
	ds_read_b32 v0, v0
	s_waitcnt lgkmcnt(1)
	v_cmp_ne_u32_e32 vcc, 0, v2
	s_cbranch_vccnz .LBB0_217
	s_add_u32 s10, s24, 0xa0200
	s_addc_u32 s11, s25, 0
	s_add_u32 s12, s24, 0xa0400
	s_addc_u32 s13, s25, 0
	s_add_u32 s14, s24, 0xa0500
	s_addc_u32 s15, s25, 0
	s_add_u32 s16, s24, 0xa0600
	s_addc_u32 s17, s25, 0
	s_add_u32 s18, s24, 0xa0700
	s_addc_u32 s19, s25, 0
	s_add_u32 s20, s24, 0xa0800
	s_addc_u32 s21, s25, 0
	s_add_u32 s22, s24, 0xa0900
	s_addc_u32 s23, s25, 0
	s_add_u32 s30, s24, 0xa0a00
	s_addc_u32 s31, s25, 0
	s_add_u32 s34, s24, 0xa0b00
	s_addc_u32 s35, s25, 0
	s_add_u32 s36, s24, 0xa0c00
	s_addc_u32 s37, s25, 0
	s_add_u32 s38, s24, 0xa0d00
	s_addc_u32 s39, s25, 0
	s_add_u32 s40, s24, 0xa0e00
	s_addc_u32 s41, s25, 0
	s_add_u32 s42, s24, 0xa0f00
	s_addc_u32 s43, s25, 0
	s_add_u32 s44, s24, 0xa1000
	s_addc_u32 s45, s25, 0
	s_add_u32 s46, s24, 0xa1100
	s_addc_u32 s47, s25, 0
	s_add_u32 s48, s24, 0xa1200
	v_readlane_b32 s0, v255, 0
	s_addc_u32 s49, s25, 0
	s_mul_i32 s4, s27, s0
	s_add_u32 s50, s24, 0xa1300
	s_mul_i32 s4, s4, s26
	s_addc_u32 s51, s25, 0
	s_mov_b32 s5, 1
	v_mov_b32_e32 v16, 0
	s_branch .LBB0_205

; __device__ __forceinline__ unsigned xb_ld(unsigned* p)              { return __hip_atomic_load(p, __ATOMIC_RELAXED, __HIP_MEMORY_SCOPE_AGENT); }
; __device__ __forceinline__ unsigned xb_add(unsigned* p, unsigned v) { return __hip_atomic_fetch_add(p, v, __ATOMIC_RELAXED, __HIP_MEMORY_SCOPE_AGENT); }
; #define XB_SPIN(cond, bar) do { unsigned _sp = 0; while (cond) { __builtin_amdgcn_s_sleep(1); \
;     if ((++_sp & 255u) == 0u) { if (xb_ld(&(bar)[XB_TMO])) break; if (_sp > XB_SPIN_CAP) { atomicAdd(&(bar)[XB_TMO], 1u); break; } } } } while (0)
; __device__ __forceinline__ void xcd_barrier(const XcdBarrier& b) {
;     ...
;         const unsigned old = xb_add(&bar[XB_XSUB(b.x)], 1u);
;         const unsigned gen = old / nloc;
;         if (old + 1u == (gen + 1u) * nloc) {
;             __builtin_amdgcn_fence(__ATOMIC_RELEASE, "agent");
;             asm volatile("s_waitcnt vmcnt(0)" ::: "memory");
;             const unsigned og = xb_add(&bar[XB_TOP], 1u);
;             const unsigned tg = og / nx;
;             if (og + 1u == (tg + 1u) * nx) xb_add(&bar[XB_TOPGEN], 1u);
;             else XB_SPIN(xb_ld(&bar[XB_TOPGEN]) == tg, bar);
;             __builtin_amdgcn_fence(__ATOMIC_ACQUIRE, "agent");
;             xb_add(&bar[XB_XGEN(b.x)], 1u);
;             asm volatile("s_waitcnt vmcnt(0)" ::: "memory");
.LBB0_217:
	s_lshl_b32 s0, s33, 8
	v_readlane_b32 s4, v255, 1
	v_readlane_b32 s5, v255, 2
	s_add_u32 s10, s4, s0
	s_addc_u32 s11, s5, 0
	v_mov_b32_e32 v3, 0x1000
	v_mov_b32_e32 v4, 1
	global_atomic_add v3, v3, v4, s[10:11] offset:1024 sc0
	s_waitcnt lgkmcnt(0)
	v_readfirstlane_b32 s12, v2
	v_readfirstlane_b32 s13, v0
	s_mul_i32 s12, s12, 2
	s_mul_i32 s13, s13, 2
	v_mov_b32_e32 v1, 0xa3400
	s_mov_b32 s1, 0
	s_waitcnt vmcnt(0)
	v_readfirstlane_b32 s0, v3
	s_add_i32 s0, s0, 1
	s_cmp_lg_u32 s0, s12
	s_cbranch_scc1 .Lgb2_poll
	global_atomic_add v1, v4, s[24:25]

; __device__ __forceinline__ void xcd_barrier(const XcdBarrier& b) {
;     asm volatile("s_waitcnt vmcnt(0)" ::: "memory");
;     __syncthreads();
;     if (threadIdx.x == 0) {
;         unsigned* bar = b.bar;
;         __builtin_amdgcn_s_waitcnt(0);
;         unsigned nloc = b.st[0], nx = b.st[1];
;         if (nloc == 0u) { xcd_barrier_complete(bar, b.x, nloc, nx); b.st[0] = nloc; b.st[1] = nx; }
.LBB0_293:
	s_waitcnt vmcnt(0)
	v_readlane_b32 s0, v255, 3
	v_readlane_b32 s1, v255, 4
	s_waitcnt vmcnt(0)
	s_barrier
	v_readfirstlane_b32 s4, v208
	s_cmp_lg_u32 s4, 64
	s_cbranch_scc1 .Lgb3_noinv
	buffer_inv sc1
	s_waitcnt vmcnt(0)
.Lgb3_noinv:
	s_and_saveexec_b64 s[8:9], s[0:1]
	s_cbranch_execz .LBB0_345
	s_add_i32 s0, 0, 0x20000
	v_mov_b32_e32 v0, s0
	s_waitcnt vmcnt(0) expcnt(0) lgkmcnt(0)
	ds_read_b32 v2, v0
	s_add_i32 s0, 0, 0x20004
	v_mov_b32_e32 v0, s0
	ds_read_b32 v0, v0
	s_waitcnt lgkmcnt(1)
	v_cmp_ne_u32_e32 vcc, 0, v2
	s_cbranch_vccnz .LBB0_309
	s_add_u32 s10, s24, 0xa0200
	s_addc_u32 s11, s25, 0
	s_add_u32 s12, s24, 0xa0400
	s_addc_u32 s13, s25, 0
	s_add_u32 s14, s24, 0xa0500
	s_addc_u32 s15, s25, 0
	s_add_u32 s16, s24, 0xa0600
	s_addc_u32 s17, s25, 0
	s_add_u32 s18, s24, 0xa0700
	s_addc_u32 s19, s25, 0
	s_add_u32 s20, s24, 0xa0800
	s_addc_u32 s21, s25, 0
	s_add_u32 s22, s24, 0xa0900
	s_addc_u32 s23, s25, 0
	s_add_u32 s30, s24, 0xa0a00
	s_addc_u32 s31, s25, 0
	s_add_u32 s34, s24, 0xa0b00
	s_addc_u32 s35, s25, 0
	s_add_u32 s36, s24, 0xa0c00
	s_addc_u32 s37, s25, 0
	s_add_u32 s38, s24, 0xa0d00
	s_addc_u32 s39, s25, 0
	s_add_u32 s40, s24, 0xa0e00
	s_addc_u32 s41, s25, 0
	s_add_u32 s42, s24, 0xa0f00
	s_addc_u32 s43, s25, 0
	s_add_u32 s44, s24, 0xa1000
	s_addc_u32 s45, s25, 0
	s_add_u32 s46, s24, 0xa1100
	s_addc_u32 s47, s25, 0
	s_add_u32 s48, s24, 0xa1200
	v_readlane_b32 s0, v255, 0
	s_addc_u32 s49, s25, 0
	s_mul_i32 s3, s27, s0
	s_add_u32 s50, s24, 0xa1300
	s_mul_i32 s3, s3, s26
	s_addc_u32 s51, s25, 0
	s_mov_b32 s4, 1
	v_mov_b32_e32 v16, 0
	s_branch .LBB0_297

; __device__ __forceinline__ unsigned xb_ld(unsigned* p)              { return __hip_atomic_load(p, __ATOMIC_RELAXED, __HIP_MEMORY_SCOPE_AGENT); }
; __device__ __forceinline__ unsigned xb_add(unsigned* p, unsigned v) { return __hip_atomic_fetch_add(p, v, __ATOMIC_RELAXED, __HIP_MEMORY_SCOPE_AGENT); }
; #define XB_SPIN(cond, bar) do { unsigned _sp = 0; while (cond) { __builtin_amdgcn_s_sleep(1); \
;     if ((++_sp & 255u) == 0u) { if (xb_ld(&(bar)[XB_TMO])) break; if (_sp > XB_SPIN_CAP) { atomicAdd(&(bar)[XB_TMO], 1u); break; } } } } while (0)
; __device__ __forceinline__ void xcd_barrier(const XcdBarrier& b) {
;     ...
;         const unsigned old = xb_add(&bar[XB_XSUB(b.x)], 1u);
;         const unsigned gen = old / nloc;
;         if (old + 1u == (gen + 1u) * nloc) {
;             __builtin_amdgcn_fence(__ATOMIC_RELEASE, "agent");
;             asm volatile("s_waitcnt vmcnt(0)" ::: "memory");
;             const unsigned og = xb_add(&bar[XB_TOP], 1u);
;             const unsigned tg = og / nx;
;             if (og + 1u == (tg + 1u) * nx) xb_add(&bar[XB_TOPGEN], 1u);
;             else XB_SPIN(xb_ld(&bar[XB_TOPGEN]) == tg, bar);
;             __builtin_amdgcn_fence(__ATOMIC_ACQUIRE, "agent");
;             xb_add(&bar[XB_XGEN(b.x)], 1u);
;             asm volatile("s_waitcnt vmcnt(0)" ::: "memory");
.LBB0_309:
	s_lshl_b32 s0, s33, 8
	v_readlane_b32 s4, v255, 1
	v_readlane_b32 s5, v255, 2
	s_add_u32 s10, s4, s0
	s_addc_u32 s11, s5, 0
	v_mov_b32_e32 v3, 0x1000
	v_mov_b32_e32 v4, 1
	global_atomic_add v3, v3, v4, s[10:11] offset:1024 sc0
	s_waitcnt lgkmcnt(0)
	v_readfirstlane_b32 s12, v2
	v_readfirstlane_b32 s13, v0
	s_mul_i32 s12, s12, 3
	s_mul_i32 s13, s13, 3
	v_mov_b32_e32 v1, 0xa3400
	s_mov_b32 s1, 0
	s_waitcnt vmcnt(0)
	v_readfirstlane_b32 s0, v3
	s_add_i32 s0, s0, 1
	s_cmp_lg_u32 s0, s12
	s_cbranch_scc1 .Lgb3_poll
	global_atomic_add v1, v4, s[24:25]

; __device__ __forceinline__ void xcd_barrier(const XcdBarrier& b) {
;     asm volatile("s_waitcnt vmcnt(0)" ::: "memory");
;     __syncthreads();
;     if (threadIdx.x == 0) {
;         unsigned* bar = b.bar;
;         __builtin_amdgcn_s_waitcnt(0);
;         unsigned nloc = b.st[0], nx = b.st[1];
;         if (nloc == 0u) { xcd_barrier_complete(bar, b.x, nloc, nx); b.st[0] = nloc; b.st[1] = nx; }
.LBB0_387:
	s_or_b64 exec, exec, s[6:7]
	s_waitcnt vmcnt(0)
	v_readlane_b32 s0, v255, 3
	v_readlane_b32 s1, v255, 4
	s_barrier
	v_readfirstlane_b32 s4, v208
	s_cmp_lg_u32 s4, 64
	s_cbranch_scc1 .Lgb4_noinv
	buffer_inv sc1
	s_waitcnt vmcnt(0)
.Lgb4_noinv:
	s_and_saveexec_b64 s[6:7], s[0:1]
	s_cbranch_execz .LBB0_439
	s_add_i32 s0, 0, 0x20000
	v_mov_b32_e32 v0, s0
	s_waitcnt vmcnt(0) expcnt(0) lgkmcnt(0)
	ds_read_b32 v2, v0
	s_add_i32 s0, 0, 0x20004
	v_mov_b32_e32 v0, s0
	ds_read_b32 v0, v0
	s_waitcnt lgkmcnt(1)
	v_cmp_ne_u32_e32 vcc, 0, v2
	s_cbranch_vccnz .LBB0_403
	s_add_u32 s8, s24, 0xa0200
	s_addc_u32 s9, s25, 0
	s_add_u32 s10, s24, 0xa0400
	s_addc_u32 s11, s25, 0
	s_add_u32 s12, s24, 0xa0500
	s_addc_u32 s13, s25, 0
	s_add_u32 s14, s24, 0xa0600
	s_addc_u32 s15, s25, 0
	s_add_u32 s16, s24, 0xa0700
	s_addc_u32 s17, s25, 0
	s_add_u32 s18, s24, 0xa0800
	s_addc_u32 s19, s25, 0
	s_add_u32 s20, s24, 0xa0900
	s_addc_u32 s21, s25, 0
	s_add_u32 s22, s24, 0xa0a00
	s_addc_u32 s23, s25, 0
	s_add_u32 s30, s24, 0xa0b00
	s_addc_u32 s31, s25, 0
	s_add_u32 s34, s24, 0xa0c00
	s_addc_u32 s35, s25, 0
	s_add_u32 s36, s24, 0xa0d00
	s_addc_u32 s37, s25, 0
	s_add_u32 s38, s24, 0xa0e00
	s_addc_u32 s39, s25, 0
	s_add_u32 s40, s24, 0xa0f00
	s_addc_u32 s41, s25, 0
	s_add_u32 s42, s24, 0xa1000
	s_addc_u32 s43, s25, 0
	s_add_u32 s44, s24, 0xa1100
	s_addc_u32 s45, s25, 0
	s_add_u32 s46, s24, 0xa1200
	v_readlane_b32 s0, v255, 0
	s_addc_u32 s47, s25, 0
	s_mul_i32 s3, s27, s0
	s_add_u32 s48, s24, 0xa1300
	s_mul_i32 s3, s3, s26
	s_addc_u32 s49, s25, 0
	s_mov_b32 s4, 1
	v_mov_b32_e32 v16, 0
	s_branch .LBB0_391

; __device__ __forceinline__ unsigned xb_ld(unsigned* p)              { return __hip_atomic_load(p, __ATOMIC_RELAXED, __HIP_MEMORY_SCOPE_AGENT); }
; __device__ __forceinline__ unsigned xb_add(unsigned* p, unsigned v) { return __hip_atomic_fetch_add(p, v, __ATOMIC_RELAXED, __HIP_MEMORY_SCOPE_AGENT); }
; #define XB_SPIN(cond, bar) do { unsigned _sp = 0; while (cond) { __builtin_amdgcn_s_sleep(1); \
;     if ((++_sp & 255u) == 0u) { if (xb_ld(&(bar)[XB_TMO])) break; if (_sp > XB_SPIN_CAP) { atomicAdd(&(bar)[XB_TMO], 1u); break; } } } } while (0)
; __device__ __forceinline__ void xcd_barrier(const XcdBarrier& b) {
;     ...
;         const unsigned old = xb_add(&bar[XB_XSUB(b.x)], 1u);
;         const unsigned gen = old / nloc;
;         if (old + 1u == (gen + 1u) * nloc) {
;             __builtin_amdgcn_fence(__ATOMIC_RELEASE, "agent");
;             asm volatile("s_waitcnt vmcnt(0)" ::: "memory");
;             const unsigned og = xb_add(&bar[XB_TOP], 1u);
;             const unsigned tg = og / nx;
;             if (og + 1u == (tg + 1u) * nx) xb_add(&bar[XB_TOPGEN], 1u);
;             else XB_SPIN(xb_ld(&bar[XB_TOPGEN]) == tg, bar);
;             __builtin_amdgcn_fence(__ATOMIC_ACQUIRE, "agent");
;             xb_add(&bar[XB_XGEN(b.x)], 1u);
;             asm volatile("s_waitcnt vmcnt(0)" ::: "memory");
.LBB0_403:
	s_lshl_b32 s0, s33, 8
	v_readlane_b32 s4, v255, 1
	v_readlane_b32 s5, v255, 2
	s_add_u32 s10, s4, s0
	s_addc_u32 s11, s5, 0
	v_mov_b32_e32 v3, 0x1000
	v_mov_b32_e32 v4, 1
	global_atomic_add v3, v3, v4, s[10:11] offset:1024 sc0
	s_waitcnt lgkmcnt(0)
	v_readfirstlane_b32 s12, v2
	v_readfirstlane_b32 s13, v0
	s_mul_i32 s12, s12, 4
	s_mul_i32 s13, s13, 4
	v_mov_b32_e32 v1, 0xa3400
	s_mov_b32 s1, 0
	s_waitcnt vmcnt(0)
	v_readfirstlane_b32 s0, v3
	s_add_i32 s0, s0, 1
	s_cmp_lg_u32 s0, s12
	s_cbranch_scc1 .Lgb4_poll
	buffer_wbl2 sc1
	s_waitcnt vmcnt(0)
	global_atomic_add v1, v4, s[24:25]

; __device__ __forceinline__ void xcd_barrier(const XcdBarrier& b) {
;     asm volatile("s_waitcnt vmcnt(0)" ::: "memory");
;     __syncthreads();
;     if (threadIdx.x == 0) {
.LBB0_497:
	s_waitcnt vmcnt(0)
	v_readlane_b32 s0, v255, 3
	v_readlane_b32 s1, v255, 4
	s_waitcnt lgkmcnt(0)
	s_barrier
	v_readfirstlane_b32 s4, v208
	s_cmp_lg_u32 s4, 64
	s_cbranch_scc1 .Lgb5_noinv
	buffer_inv sc1
	s_waitcnt vmcnt(0)

; __device__ __forceinline__ unsigned xb_ld(unsigned* p)              { return __hip_atomic_load(p, __ATOMIC_RELAXED, __HIP_MEMORY_SCOPE_AGENT); }
; __device__ __forceinline__ unsigned xb_add(unsigned* p, unsigned v) { return __hip_atomic_fetch_add(p, v, __ATOMIC_RELAXED, __HIP_MEMORY_SCOPE_AGENT); }
; #define XB_SPIN(cond, bar) do { unsigned _sp = 0; while (cond) { __builtin_amdgcn_s_sleep(1); \
;     if ((++_sp & 255u) == 0u) { if (xb_ld(&(bar)[XB_TMO])) break; if (_sp > XB_SPIN_CAP) { atomicAdd(&(bar)[XB_TMO], 1u); break; } } } } while (0)
; __device__ __forceinline__ void xcd_barrier(const XcdBarrier& b) {
;     ...
;         const unsigned old = xb_add(&bar[XB_XSUB(b.x)], 1u);
;         const unsigned gen = old / nloc;
;         if (old + 1u == (gen + 1u) * nloc) {
;             __builtin_amdgcn_fence(__ATOMIC_RELEASE, "agent");
;             asm volatile("s_waitcnt vmcnt(0)" ::: "memory");
;             const unsigned og = xb_add(&bar[XB_TOP], 1u);
;             const unsigned tg = og / nx;
;             if (og + 1u == (tg + 1u) * nx) xb_add(&bar[XB_TOPGEN], 1u);
;             else XB_SPIN(xb_ld(&bar[XB_TOPGEN]) == tg, bar);
;             __builtin_amdgcn_fence(__ATOMIC_ACQUIRE, "agent");
;             xb_add(&bar[XB_XGEN(b.x)], 1u);
;             asm volatile("s_waitcnt vmcnt(0)" ::: "memory");
.LBB0_513:
	s_lshl_b32 s0, s33, 8
	v_readlane_b32 s4, v255, 1
	v_readlane_b32 s5, v255, 2
	s_add_u32 s10, s4, s0
	s_addc_u32 s11, s5, 0
	v_mov_b32_e32 v3, 0x1000
	v_mov_b32_e32 v4, 1
	global_atomic_add v3, v3, v4, s[10:11] offset:1024 sc0
	s_waitcnt lgkmcnt(0)
	v_readfirstlane_b32 s12, v2
	v_readfirstlane_b32 s13, v0
	s_mul_i32 s12, s12, 5
	s_mul_i32 s13, s13, 5
	v_mov_b32_e32 v1, 0xa3400
	s_mov_b32 s1, 0
	s_waitcnt vmcnt(0)
	v_readfirstlane_b32 s0, v3
	s_add_i32 s0, s0, 1
	s_cmp_lg_u32 s0, s12
	s_cbranch_scc1 .Lgb5_poll
	global_atomic_add v1, v4, s[24:25]

; __device__ __forceinline__ void xcd_barrier(const XcdBarrier& b) {
;     asm volatile("s_waitcnt vmcnt(0)" ::: "memory");
;     __syncthreads();
;     if (threadIdx.x == 0) {
;         unsigned* bar = b.bar;
;         __builtin_amdgcn_s_waitcnt(0);
;         unsigned nloc = b.st[0], nx = b.st[1];
;         if (nloc == 0u) { xcd_barrier_complete(bar, b.x, nloc, nx); b.st[0] = nloc; b.st[1] = nx; }
.LBB0_601:
	s_waitcnt vmcnt(0)
	s_waitcnt vmcnt(0)
	s_barrier
	v_readfirstlane_b32 s4, v208
	s_cmp_lg_u32 s4, 64
	s_cbranch_scc1 .Lgb6_noinv
	buffer_inv sc1
	s_waitcnt vmcnt(0)
.Lgb6_noinv:
	s_mov_b64 s[8:9], exec
	v_readlane_b32 s0, v255, 3
	v_readlane_b32 s1, v255, 4
	s_and_b64 s[0:1], s[8:9], s[0:1]
	s_mov_b64 exec, s[0:1]
	s_cbranch_execz .LBB0_653
	s_add_i32 s0, 0, 0x20000
	v_mov_b32_e32 v0, s0
	s_waitcnt vmcnt(0) expcnt(0) lgkmcnt(0)
	ds_read_b32 v2, v0
	s_add_i32 s0, 0, 0x20004
	v_mov_b32_e32 v0, s0
	ds_read_b32 v0, v0
	s_waitcnt lgkmcnt(1)
	v_cmp_ne_u32_e32 vcc, 0, v2
	s_cbranch_vccnz .LBB0_617
	s_add_u32 s4, s24, 0xa0200
	s_addc_u32 s5, s25, 0
	s_add_u32 s10, s24, 0xa0400
	s_addc_u32 s11, s25, 0
	s_add_u32 s12, s24, 0xa0500
	s_addc_u32 s13, s25, 0
	s_add_u32 s14, s24, 0xa0600
	s_addc_u32 s15, s25, 0
	s_add_u32 s16, s24, 0xa0700
	s_addc_u32 s17, s25, 0
	s_add_u32 s18, s24, 0xa0800
	s_addc_u32 s19, s25, 0
	s_add_u32 s20, s24, 0xa0900
	s_addc_u32 s21, s25, 0
	s_add_u32 s22, s24, 0xa0a00
	s_addc_u32 s23, s25, 0
	s_add_u32 s30, s24, 0xa0b00
	s_addc_u32 s31, s25, 0
	s_add_u32 s34, s24, 0xa0c00
	s_addc_u32 s35, s25, 0
	s_add_u32 s36, s24, 0xa0d00
	s_addc_u32 s37, s25, 0
	s_add_u32 s38, s24, 0xa0e00
	s_addc_u32 s39, s25, 0
	s_add_u32 s40, s24, 0xa0f00
	s_addc_u32 s41, s25, 0
	s_add_u32 s42, s24, 0xa1000
	s_addc_u32 s43, s25, 0
	s_add_u32 s44, s24, 0xa1100
	s_addc_u32 s45, s25, 0
	s_add_u32 s46, s24, 0xa1200
	v_readlane_b32 s0, v255, 0
	s_addc_u32 s47, s25, 0
	s_mul_i32 s3, s27, s0
	s_add_u32 s48, s24, 0xa1300
	s_mul_i32 s3, s3, s26
	s_addc_u32 s49, s25, 0
	s_mov_b32 s6, 1
	v_mov_b32_e32 v16, 0
	s_branch .LBB0_605

; __device__ __forceinline__ unsigned xb_ld(unsigned* p)              { return __hip_atomic_load(p, __ATOMIC_RELAXED, __HIP_MEMORY_SCOPE_AGENT); }
; __device__ __forceinline__ unsigned xb_add(unsigned* p, unsigned v) { return __hip_atomic_fetch_add(p, v, __ATOMIC_RELAXED, __HIP_MEMORY_SCOPE_AGENT); }
; #define XB_SPIN(cond, bar) do { unsigned _sp = 0; while (cond) { __builtin_amdgcn_s_sleep(1); \
;     if ((++_sp & 255u) == 0u) { if (xb_ld(&(bar)[XB_TMO])) break; if (_sp > XB_SPIN_CAP) { atomicAdd(&(bar)[XB_TMO], 1u); break; } } } } while (0)
; __device__ __forceinline__ void xcd_barrier(const XcdBarrier& b) {
;     ...
;         const unsigned old = xb_add(&bar[XB_XSUB(b.x)], 1u);
;         const unsigned gen = old / nloc;
;         if (old + 1u == (gen + 1u) * nloc) {
;             __builtin_amdgcn_fence(__ATOMIC_RELEASE, "agent");
;             asm volatile("s_waitcnt vmcnt(0)" ::: "memory");
;             const unsigned og = xb_add(&bar[XB_TOP], 1u);
;             const unsigned tg = og / nx;
;             if (og + 1u == (tg + 1u) * nx) xb_add(&bar[XB_TOPGEN], 1u);
;             else XB_SPIN(xb_ld(&bar[XB_TOPGEN]) == tg, bar);
;             __builtin_amdgcn_fence(__ATOMIC_ACQUIRE, "agent");
;             xb_add(&bar[XB_XGEN(b.x)], 1u);
;             asm volatile("s_waitcnt vmcnt(0)" ::: "memory");
.LBB0_617:
	s_lshl_b32 s0, s33, 8
	v_readlane_b32 s4, v255, 1
	v_readlane_b32 s5, v255, 2
	s_add_u32 s10, s4, s0
	s_addc_u32 s11, s5, 0
	v_mov_b32_e32 v3, 0x1000
	v_mov_b32_e32 v4, 1
	global_atomic_add v3, v3, v4, s[10:11] offset:1024 sc0
	s_waitcnt lgkmcnt(0)
	v_readfirstlane_b32 s12, v2
	v_readfirstlane_b32 s13, v0
	s_mul_i32 s12, s12, 6
	s_mul_i32 s13, s13, 6
	v_mov_b32_e32 v1, 0xa3400
	s_mov_b32 s1, 0
	s_waitcnt vmcnt(0)
	v_readfirstlane_b32 s0, v3
	s_add_i32 s0, s0, 1
	s_cmp_lg_u32 s0, s12
	s_cbranch_scc1 .Lgb6_poll
	buffer_wbl2 sc1
	s_waitcnt vmcnt(0)
	global_atomic_add v1, v4, s[24:25]
